# v92 plus prologue: the 32 extra adaLN GEMV units moved to workgroups 224-255 (4 conversion items per wave instead of 5)
# speedup vs baseline: 1.0066x; 1.0028x over previous
.LBB0_768:
	s_or_b64 exec, exec, s[2:3]
	s_ashr_i32 s0, s4, 6
	v_and_b32_e32 v1, 63, v0
	s_cmpk_gt_i32 s31, 0x11f
	s_mov_b32 s48, 0x16000
	s_waitcnt lgkmcnt(0)
	s_barrier
	s_cbranch_scc1 .LBB0_776
	s_movk_i32 s2, 0x480
	v_and_b32_e32 v6, 0x7f, v0
	s_lshl_b32 s1, s0, 7
	v_lshlrev_b32_e32 v4, 1, v1
	v_lshl_add_u32 v5, v1, 3, 0
	v_cmp_gt_i32_e32 vcc, s2, v0
	s_mul_i32 s2, s0, 0x1200
	v_lshlrev_b32_e32 v128, 2, v6
	s_mul_i32 s3, s0, 0x1800
	s_ashr_i32 s4, s1, 31
	v_add_u32_e32 v28, 0, v128
	s_waitcnt vmcnt(0)
	v_lshl_add_u64 v[2:3], s[34:35], 0, v[128:129]
	s_add_i32 s5, s3, 0
	v_lshlrev_b32_e32 v128, 2, v4
	v_add_u32_e32 v29, s2, v5
	v_lshlrev_b32_e32 v4, 2, v6
	s_xor_b32 s12, s31, 0xe0
	s_branch .LBB0_771
